# S5 stage-3: epilogue U values prefetched at second-direction start, start-state load issued with the coefficient loads (one round trip per direction)
# speedup vs baseline: 1.0115x; 1.0006x over previous
.LBB0_1521:
	s_or_b64 exec, exec, s[4:5]
	v_lshl_or_b32 v176, s10, 12, v200
	v_lshl_add_u64 v[238:239], v[186:187], 0, v[176:177]
	v_lshl_add_u64 v[112:113], v[188:189], 0, v[176:177]
	global_load_dwordx4 v[214:217], v[238:239], off
	global_load_dwordx4 v[218:221], v[112:113], off
	global_load_dwordx4 v[222:225], v[238:239], off offset:64
	global_load_dwordx4 v[226:229], v[112:113], off offset:64
	global_load_dwordx4 v[230:233], v[238:239], off offset:128
	global_load_dwordx4 v[234:237], v[112:113], off offset:128
	global_load_dwordx4 v[76:79], v[238:239], off offset:192
	global_load_dwordx4 v[116:119], v[112:113], off offset:192
	s_or_b32 s4, s9, 1
	s_ashr_i32 s5, s4, 31
	s_lshl_b64 s[4:5], s[4:5], 15
	v_lshl_add_u64 v[128:129], v[192:193], 0, s[4:5]
	global_load_dwordx2 v[128:129], v[128:129], off
	s_waitcnt vmcnt(7)
	v_xor_b32_e32 v218, 0x80000000, v218
	v_xor_b32_e32 v219, 0x80000000, v219
	v_xor_b32_e32 v220, 0x80000000, v220
	v_xor_b32_e32 v221, 0x80000000, v221
	v_cvt_pk_bf16_f32 v60, v214, v218
	v_cvt_pk_bf16_f32 v61, v215, v219
	v_cvt_pk_bf16_f32 v62, v216, v220
	v_cvt_pk_bf16_f32 v63, v217, v221
	s_waitcnt vmcnt(5)
	v_xor_b32_e32 v226, 0x80000000, v226
	v_xor_b32_e32 v227, 0x80000000, v227
	v_xor_b32_e32 v228, 0x80000000, v228
	v_xor_b32_e32 v229, 0x80000000, v229
	v_cvt_pk_bf16_f32 v56, v222, v226
	v_cvt_pk_bf16_f32 v57, v223, v227
	v_cvt_pk_bf16_f32 v58, v224, v228
	v_cvt_pk_bf16_f32 v59, v225, v229
	s_waitcnt vmcnt(3)
	v_xor_b32_e32 v234, 0x80000000, v234
	v_xor_b32_e32 v235, 0x80000000, v235
	v_xor_b32_e32 v236, 0x80000000, v236
	v_xor_b32_e32 v237, 0x80000000, v237
	v_cvt_pk_bf16_f32 v72, v230, v234
	v_cvt_pk_bf16_f32 v73, v231, v235
	v_cvt_pk_bf16_f32 v74, v232, v236
	v_cvt_pk_bf16_f32 v75, v233, v237
	s_waitcnt vmcnt(1)
	v_xor_b32_e32 v116, 0x80000000, v116
	v_xor_b32_e32 v117, 0x80000000, v117
	v_xor_b32_e32 v118, 0x80000000, v118
	v_xor_b32_e32 v119, 0x80000000, v119
	v_cvt_pk_bf16_f32 v76, v76, v116
	v_cvt_pk_bf16_f32 v77, v77, v117
	v_cvt_pk_bf16_f32 v78, v78, v118
	v_cvt_pk_bf16_f32 v79, v79, v119
	v_mov_b32_e32 v232, s8
	v_or_b32_e32 v230, s7, v194
	v_lshlrev_b32_e32 v232, 5, v232
	v_lshlrev_b32_e32 v230, 11, v230
	v_lshl_add_u32 v231, v173, 1, v232
	v_add_u32_e32 v230, v230, v231
	v_add_u32_e32 v231, 0x1000, v230
	v_add_u32_e32 v232, 0x8000, v230
	v_add_u32_e32 v233, 0x9000, v230
	v_add_u32_e32 v234, 0x10000, v230
	v_add_u32_e32 v235, 0x11000, v230
	v_add_u32_e32 v236, 0x18000, v230
	v_add_u32_e32 v237, 0x19000, v230
	global_load_ushort v214, v230, s[60:61]
	global_load_ushort v215, v230, s[60:61] offset:2048
	global_load_ushort v216, v231, s[60:61]
	global_load_ushort v217, v231, s[60:61] offset:2048
	global_load_ushort v218, v232, s[60:61]
	global_load_ushort v219, v232, s[60:61] offset:2048
	global_load_ushort v220, v233, s[60:61]
	global_load_ushort v221, v233, s[60:61] offset:2048
	global_load_ushort v222, v234, s[60:61]
	global_load_ushort v223, v234, s[60:61] offset:2048
	global_load_ushort v224, v235, s[60:61]
	global_load_ushort v225, v235, s[60:61] offset:2048
	global_load_ushort v226, v236, s[60:61]
	global_load_ushort v227, v236, s[60:61] offset:2048
	global_load_ushort v228, v237, s[60:61]
	global_load_ushort v229, v237, s[60:61] offset:2048
	v_mfma_f32_16x16x32_bf16 v[80:83], v[12:15], v[32:35], 0
	s_add_i32 s6, s6, s28
	s_cmpk_gt_i32 s6, 0x5fff
	v_mfma_f32_16x16x32_bf16 v[84:87], v[12:15], v[36:39], 0
	v_mfma_f32_16x16x32_bf16 v[88:91], v[12:15], v[40:43], 0
	v_mfma_f32_16x16x32_bf16 v[92:95], v[12:15], v[44:47], 0
	v_mfma_f32_16x16x32_bf16 v[96:99], v[12:15], v[48:51], 0
	v_mfma_f32_16x16x32_bf16 v[100:103], v[12:15], v[52:55], 0
	v_mfma_f32_16x16x32_bf16 v[120:123], v[12:15], v[64:67], 0
	v_mfma_f32_16x16x32_bf16 v[124:127], v[12:15], v[68:71], 0
	ds_write_b128 v201, v[80:83]
	ds_write_b128 v201, v[84:87] offset:1280
	s_nop 0
	ds_write_b128 v201, v[88:91] offset:2560
	ds_write_b128 v202, v[92:95]
	ds_write_b128 v201, v[96:99] offset:5120
	ds_write_b128 v201, v[100:103] offset:6400
	ds_write_b128 v201, v[120:123] offset:7680
	ds_write_b128 v203, v[124:127]
	s_waitcnt lgkmcnt(0)
	ds_read_b128 v[12:15], v175 offset:48
	ds_read_b128 v[80:83], v175 offset:5168
	v_mfma_f32_16x16x32_bf16 v[132:135], v[8:11], v[32:35], 0
	s_waitcnt vmcnt(16) lgkmcnt(1)
	v_fma_f32 v15, -v169, v129, v15
	s_waitcnt lgkmcnt(0)
	v_fma_f32 v83, v169, v128, v83
	v_fmac_f32_e32 v15, v168, v128
	v_fmac_f32_e32 v83, v168, v129
	v_fma_f32 v14, -v169, v83, v14
	v_cvt_pk_bf16_f32 v84, v15, v83
	v_fmac_f32_e32 v14, v168, v15
	v_fma_f32 v15, v169, v15, v82
	ds_write_b32 v205, v84 offset:14320
	v_fmac_f32_e32 v15, v168, v83
	v_fma_f32 v13, -v169, v15, v13
	v_fma_f32 v81, v169, v14, v81
	v_fmac_f32_e32 v81, v168, v15
	v_cvt_pk_bf16_f32 v82, v14, v15
	v_fmac_f32_e32 v13, v168, v14
	v_fma_f32 v86, -v169, v81, v12
	ds_write_b32 v205, v82 offset:14048
	v_mfma_f32_16x16x32_bf16 v[136:139], v[8:11], v[36:39], 0
	v_cvt_pk_bf16_f32 v12, v13, v81
	v_fmac_f32_e32 v86, v168, v13
	v_fmac_f32_e32 v80, v169, v13
	ds_write_b32 v205, v12 offset:13776
	v_fmac_f32_e32 v80, v168, v81
	v_mfma_f32_16x16x32_bf16 v[140:143], v[8:11], v[40:43], 0
	v_cvt_pk_bf16_f32 v12, v86, v80
	ds_write_b32 v205, v12 offset:13504
	ds_read_b128 v[12:15], v175 offset:32
	ds_read_b128 v[82:85], v175 offset:5152
	v_mfma_f32_16x16x32_bf16 v[144:147], v[8:11], v[44:47], 0
	s_waitcnt lgkmcnt(1)
	v_fma_f32 v15, -v169, v80, v15
	s_waitcnt lgkmcnt(0)
	v_fma_f32 v81, v169, v86, v85
	v_fmac_f32_e32 v15, v168, v86
	v_fmac_f32_e32 v81, v168, v80
	v_fma_f32 v14, -v169, v81, v14
	v_cvt_pk_bf16_f32 v80, v15, v81
	v_fmac_f32_e32 v14, v168, v15
	v_fma_f32 v15, v169, v15, v84
	ds_write_b32 v205, v80 offset:13232
	v_fmac_f32_e32 v15, v168, v81
	v_fma_f32 v13, -v169, v15, v13
	v_fma_f32 v81, v169, v14, v83
	v_cvt_pk_bf16_f32 v80, v14, v15
	v_fmac_f32_e32 v81, v168, v15
	ds_write_b32 v205, v80 offset:12960
	v_fmac_f32_e32 v13, v168, v14
	v_fma_f32 v80, -v169, v81, v12
	v_mfma_f32_16x16x32_bf16 v[148:151], v[8:11], v[48:51], 0
	v_cvt_pk_bf16_f32 v12, v13, v81
	v_fmac_f32_e32 v80, v168, v13
	v_fmac_f32_e32 v82, v169, v13
	ds_write_b32 v205, v12 offset:12688
	v_fmac_f32_e32 v82, v168, v81
	v_mfma_f32_16x16x32_bf16 v[152:155], v[8:11], v[52:55], 0
	v_cvt_pk_bf16_f32 v12, v80, v82
	ds_write_b32 v205, v12 offset:12416
	ds_read_b128 v[12:15], v175 offset:16
	ds_read_b128 v[84:87], v175 offset:5136
	v_mfma_f32_16x16x32_bf16 v[156:159], v[8:11], v[64:67], 0
	s_waitcnt lgkmcnt(1)
	v_fma_f32 v15, -v169, v82, v15
	s_waitcnt lgkmcnt(0)
	v_fma_f32 v81, v169, v80, v87
	v_fmac_f32_e32 v15, v168, v80
	v_fmac_f32_e32 v81, v168, v82
	v_fma_f32 v14, -v169, v81, v14
	v_cvt_pk_bf16_f32 v80, v15, v81
	v_fmac_f32_e32 v14, v168, v15
	v_fma_f32 v15, v169, v15, v86
	ds_write_b32 v205, v80 offset:12144
	v_fmac_f32_e32 v15, v168, v81
	v_fma_f32 v13, -v169, v15, v13
	v_fma_f32 v81, v169, v14, v85
	v_cvt_pk_bf16_f32 v80, v14, v15
	v_fmac_f32_e32 v81, v168, v15
	ds_write_b32 v205, v80 offset:11872
	v_fmac_f32_e32 v13, v168, v14
	v_fma_f32 v80, -v169, v81, v12
	v_mfma_f32_16x16x32_bf16 v[160:163], v[8:11], v[68:71], 0
	v_cvt_pk_bf16_f32 v12, v13, v81
	v_fmac_f32_e32 v80, v168, v13
	v_fmac_f32_e32 v84, v169, v13
	ds_write_b32 v205, v12 offset:11600
	v_fmac_f32_e32 v84, v168, v81
	v_mfma_f32_16x16x32_bf16 v[104:107], v[4:7], v[32:35], 0
	v_cvt_pk_bf16_f32 v12, v80, v84
	ds_write_b32 v205, v12 offset:11328
	ds_read_b128 v[12:15], v175
	ds_read_b128 v[92:95], v175 offset:5120
	v_mfma_f32_16x16x32_bf16 v[108:111], v[4:7], v[36:39], 0
	s_waitcnt lgkmcnt(1)
	v_fma_f32 v15, -v169, v84, v15
	s_waitcnt lgkmcnt(0)
	v_fma_f32 v81, v169, v80, v95
	v_fmac_f32_e32 v15, v168, v80
	v_fmac_f32_e32 v81, v168, v84
	v_fma_f32 v14, -v169, v81, v14
	v_cvt_pk_bf16_f32 v80, v15, v81
	v_fmac_f32_e32 v14, v168, v15
	v_fma_f32 v15, v169, v15, v94
	ds_write_b32 v205, v80 offset:11056
	v_fmac_f32_e32 v15, v168, v81
	v_fma_f32 v13, -v169, v15, v13
	v_fma_f32 v81, v169, v14, v93
	v_fmac_f32_e32 v81, v168, v15
	v_cvt_pk_bf16_f32 v80, v14, v15
	v_fmac_f32_e32 v13, v168, v14
	v_fma_f32 v93, -v169, v81, v12
	ds_write_b32 v205, v80 offset:10784
	v_mfma_f32_16x16x32_bf16 v[112:115], v[4:7], v[40:43], 0
	v_cvt_pk_bf16_f32 v12, v13, v81
	v_fmac_f32_e32 v93, v168, v13
	v_fmac_f32_e32 v92, v169, v13
	ds_write_b32 v205, v12 offset:10512
	v_fmac_f32_e32 v92, v168, v81
	v_mfma_f32_16x16x32_bf16 v[116:119], v[4:7], v[44:47], 0
	v_cvt_pk_bf16_f32 v12, v93, v92
	ds_write_b32 v205, v12 offset:10240
	s_waitcnt lgkmcnt(0)
	ds_read_b128 v[88:91], v204 offset:10240
	ds_read_b128 v[84:87], v204 offset:10304
	ds_read_b128 v[80:83], v204 offset:10368
	ds_read_b128 v[12:15], v204 offset:10432
	s_waitcnt lgkmcnt(0)
	ds_write_b128 v201, v[132:135]
	ds_write_b128 v201, v[136:139] offset:1280
	ds_write_b128 v201, v[140:143] offset:2560
	ds_write_b128 v202, v[144:147]
	ds_write_b128 v201, v[148:151] offset:5120
	ds_write_b128 v201, v[152:155] offset:6400
	ds_write_b128 v201, v[156:159] offset:7680
	ds_write_b128 v203, v[160:163]
	s_waitcnt lgkmcnt(0)
	ds_read_b128 v[94:97], v175 offset:48
	ds_read_b128 v[8:11], v175 offset:5168
	v_mfma_f32_16x16x32_bf16 v[120:123], v[4:7], v[48:51], 0
	s_waitcnt lgkmcnt(1)
	v_fma_f32 v97, -v169, v92, v97
	s_waitcnt lgkmcnt(0)
	v_fma_f32 v11, v169, v93, v11
	v_fmac_f32_e32 v11, v168, v92
	v_fmac_f32_e32 v97, v168, v93
	v_fma_f32 v92, -v169, v11, v96
	v_mfma_f32_16x16x32_bf16 v[124:127], v[4:7], v[52:55], 0
	v_cvt_pk_bf16_f32 v93, v97, v11
	v_fmac_f32_e32 v92, v168, v97
	v_fma_f32 v10, v169, v97, v10
	ds_write_b32 v205, v93 offset:14320
	v_fmac_f32_e32 v10, v168, v11
	v_fma_f32 v93, -v169, v10, v95
	v_fma_f32 v9, v169, v92, v9
	v_fmac_f32_e32 v9, v168, v10
	v_cvt_pk_bf16_f32 v11, v92, v10
	v_fmac_f32_e32 v93, v168, v92
	v_fma_f32 v10, -v169, v9, v94
	ds_write_b32 v205, v11 offset:14048
	v_mfma_f32_16x16x32_bf16 v[128:131], v[4:7], v[64:67], 0
	v_cvt_pk_bf16_f32 v11, v93, v9
	v_fmac_f32_e32 v10, v168, v93
	v_fmac_f32_e32 v8, v169, v93
	ds_write_b32 v205, v11 offset:13776
	v_fmac_f32_e32 v8, v168, v9
	v_mfma_f32_16x16x32_bf16 v[164:167], v[4:7], v[68:71], 0
	v_cvt_pk_bf16_f32 v9, v10, v8
	ds_write_b32 v205, v9 offset:13504
	ds_read_b128 v[92:95], v175 offset:32
	ds_read_b128 v[96:99], v175 offset:5152
	v_mfma_f32_16x16x32_bf16 v[132:135], v[0:3], v[32:35], 0
	s_waitcnt lgkmcnt(1)
	v_fma_f32 v9, -v169, v8, v95
	s_waitcnt lgkmcnt(0)
	v_fma_f32 v11, v169, v10, v99
	v_fmac_f32_e32 v9, v168, v10
	v_fmac_f32_e32 v11, v168, v8
	v_fma_f32 v8, -v169, v11, v94
	v_cvt_pk_bf16_f32 v10, v9, v11
	v_fmac_f32_e32 v8, v168, v9
	v_fma_f32 v9, v169, v9, v98
	v_fmac_f32_e32 v9, v168, v11
	ds_write_b32 v205, v10 offset:13232
	v_fma_f32 v11, -v169, v9, v93
	v_fma_f32 v93, v169, v8, v97
	v_fmac_f32_e32 v93, v168, v9
	v_cvt_pk_bf16_f32 v10, v8, v9
	v_fmac_f32_e32 v11, v168, v8
	v_fma_f32 v97, -v169, v93, v92
	ds_write_b32 v205, v10 offset:12960
	v_mfma_f32_16x16x32_bf16 v[136:139], v[0:3], v[36:39], 0
	v_cvt_pk_bf16_f32 v8, v11, v93
	v_fmac_f32_e32 v97, v168, v11
	v_fmac_f32_e32 v96, v169, v11
	ds_write_b32 v205, v8 offset:12688
	v_fmac_f32_e32 v96, v168, v93
	v_mfma_f32_16x16x32_bf16 v[140:143], v[0:3], v[40:43], 0
	v_cvt_pk_bf16_f32 v8, v97, v96
	ds_write_b32 v205, v8 offset:12416
	ds_read_b128 v[8:11], v175 offset:16
	ds_read_b128 v[92:95], v175 offset:5136
	v_mfma_f32_16x16x32_bf16 v[148:151], v[0:3], v[44:47], 0
	s_waitcnt lgkmcnt(1)
	v_fma_f32 v11, -v169, v96, v11
	s_waitcnt lgkmcnt(0)
	v_fma_f32 v95, v169, v97, v95
	v_fmac_f32_e32 v11, v168, v97
	v_fmac_f32_e32 v95, v168, v96
	v_fma_f32 v10, -v169, v95, v10
	v_cvt_pk_bf16_f32 v96, v11, v95
	v_fmac_f32_e32 v10, v168, v11
	v_fma_f32 v11, v169, v11, v94
	ds_write_b32 v205, v96 offset:12144
	v_fmac_f32_e32 v11, v168, v95
	v_fma_f32 v9, -v169, v11, v9
	v_fma_f32 v93, v169, v10, v93
	v_cvt_pk_bf16_f32 v94, v10, v11
	v_fmac_f32_e32 v93, v168, v11
	ds_write_b32 v205, v94 offset:11872
	v_fmac_f32_e32 v9, v168, v10
	v_fma_f32 v94, -v169, v93, v8
	s_nop 0
	v_cvt_pk_bf16_f32 v8, v9, v93
	v_fmac_f32_e32 v94, v168, v9
	v_fmac_f32_e32 v92, v169, v9
	ds_write_b32 v205, v8 offset:11600
	v_fmac_f32_e32 v92, v168, v93
	s_nop 0
	v_cvt_pk_bf16_f32 v8, v94, v92
	ds_write_b32 v205, v8 offset:11328
	ds_read_b128 v[8:11], v175
	ds_read_b128 v[144:147], v175 offset:5120
	s_waitcnt lgkmcnt(1)
	v_fma_f32 v11, -v169, v92, v11
	s_waitcnt lgkmcnt(0)
	v_fma_f32 v93, v169, v94, v147
	v_fmac_f32_e32 v11, v168, v94
	v_fmac_f32_e32 v93, v168, v92
	v_fma_f32 v10, -v169, v93, v10
	v_cvt_pk_bf16_f32 v92, v11, v93
	v_fmac_f32_e32 v10, v168, v11
	v_fma_f32 v11, v169, v11, v146
	ds_write_b32 v205, v92 offset:11056
	v_fmac_f32_e32 v11, v168, v93
	v_fma_f32 v9, -v169, v11, v9
	v_fma_f32 v93, v169, v10, v145
	v_fmac_f32_e32 v93, v168, v11
	v_cvt_pk_bf16_f32 v92, v10, v11
	v_fmac_f32_e32 v9, v168, v10
	v_fma_f32 v145, -v169, v93, v8
	ds_write_b32 v205, v92 offset:10784
	s_nop 0
	v_cvt_pk_bf16_f32 v8, v9, v93
	v_fmac_f32_e32 v145, v168, v9
	v_fmac_f32_e32 v144, v169, v9
	ds_write_b32 v205, v8 offset:10512
	v_fmac_f32_e32 v144, v168, v93
	s_nop 0
	v_cvt_pk_bf16_f32 v8, v145, v144
	ds_write_b32 v205, v8 offset:10240
	s_waitcnt lgkmcnt(0)
	ds_read_b128 v[100:103], v204 offset:10240
	ds_read_b128 v[96:99], v204 offset:10304
	ds_read_b128 v[92:95], v204 offset:10368
	ds_read_b128 v[8:11], v204 offset:10432
	s_waitcnt lgkmcnt(0)
	ds_write_b128 v201, v[104:107]
	ds_write_b128 v201, v[108:111] offset:1280
	ds_write_b128 v201, v[112:115] offset:2560
	ds_write_b128 v202, v[116:119]
	ds_write_b128 v201, v[120:123] offset:5120
	ds_write_b128 v201, v[124:127] offset:6400
	ds_write_b128 v201, v[128:131] offset:7680
	ds_write_b128 v203, v[164:167]
	s_waitcnt lgkmcnt(0)
	ds_read_b128 v[4:7], v175 offset:48
	ds_read_b128 v[104:107], v175 offset:5168
	v_mfma_f32_16x16x32_bf16 v[116:119], v[0:3], v[48:51], 0
	s_waitcnt lgkmcnt(1)
	v_fma_f32 v7, -v169, v144, v7
	s_waitcnt lgkmcnt(0)
	v_fma_f32 v107, v169, v145, v107
	v_fmac_f32_e32 v7, v168, v145
	v_fmac_f32_e32 v107, v168, v144
	v_fma_f32 v6, -v169, v107, v6
	v_cvt_pk_bf16_f32 v108, v7, v107
	v_fmac_f32_e32 v6, v168, v7
	v_fma_f32 v7, v169, v7, v106
	ds_write_b32 v205, v108 offset:14320
	v_fmac_f32_e32 v7, v168, v107
	v_fma_f32 v5, -v169, v7, v5
	v_fma_f32 v105, v169, v6, v105
	v_fmac_f32_e32 v105, v168, v7
	v_cvt_pk_bf16_f32 v106, v6, v7
	v_fmac_f32_e32 v5, v168, v6
	v_fma_f32 v110, -v169, v105, v4
	ds_write_b32 v205, v106 offset:14048
	v_mfma_f32_16x16x32_bf16 v[120:123], v[0:3], v[52:55], 0
	v_cvt_pk_bf16_f32 v4, v5, v105
	v_fmac_f32_e32 v110, v168, v5
	v_fmac_f32_e32 v104, v169, v5
	ds_write_b32 v205, v4 offset:13776
	v_fmac_f32_e32 v104, v168, v105
	v_mfma_f32_16x16x32_bf16 v[124:127], v[0:3], v[64:67], 0
	v_cvt_pk_bf16_f32 v4, v110, v104
	ds_write_b32 v205, v4 offset:13504
	ds_read_b128 v[4:7], v175 offset:32
	ds_read_b128 v[106:109], v175 offset:5152
	v_mfma_f32_16x16x32_bf16 v[144:147], v[0:3], v[68:71], 0
	s_waitcnt lgkmcnt(1)
	v_fma_f32 v7, -v169, v104, v7
	s_waitcnt lgkmcnt(0)
	v_fma_f32 v105, v169, v110, v109
	v_fmac_f32_e32 v7, v168, v110
	v_fmac_f32_e32 v105, v168, v104
	v_fma_f32 v6, -v169, v105, v6
	v_cvt_pk_bf16_f32 v104, v7, v105
	v_fmac_f32_e32 v6, v168, v7
	v_fma_f32 v7, v169, v7, v108
	ds_write_b32 v205, v104 offset:13232
	v_fmac_f32_e32 v7, v168, v105
	v_fma_f32 v5, -v169, v7, v5
	v_fma_f32 v105, v169, v6, v107
	v_cvt_pk_bf16_f32 v104, v6, v7
	v_fmac_f32_e32 v105, v168, v7
	ds_write_b32 v205, v104 offset:12960
	v_fmac_f32_e32 v5, v168, v6
	v_fma_f32 v104, -v169, v105, v4
	s_nop 0
	v_cvt_pk_bf16_f32 v4, v5, v105
	v_fmac_f32_e32 v104, v168, v5
	v_fmac_f32_e32 v106, v169, v5
	ds_write_b32 v205, v4 offset:12688
	v_fmac_f32_e32 v106, v168, v105
	s_nop 0
	v_cvt_pk_bf16_f32 v4, v104, v106
	ds_write_b32 v205, v4 offset:12416
	ds_read_b128 v[4:7], v175 offset:16
	ds_read_b128 v[108:111], v175 offset:5136
	s_waitcnt lgkmcnt(1)
	v_fma_f32 v7, -v169, v106, v7
	s_waitcnt lgkmcnt(0)
	v_fma_f32 v105, v169, v104, v111
	v_fmac_f32_e32 v7, v168, v104
	v_fmac_f32_e32 v105, v168, v106
	v_fma_f32 v6, -v169, v105, v6
	v_cvt_pk_bf16_f32 v104, v7, v105
	v_fmac_f32_e32 v6, v168, v7
	v_fma_f32 v7, v169, v7, v110
	ds_write_b32 v205, v104 offset:12144
	v_fmac_f32_e32 v7, v168, v105
	v_fma_f32 v5, -v169, v7, v5
	v_fma_f32 v105, v169, v6, v109
	v_cvt_pk_bf16_f32 v104, v6, v7
	v_fmac_f32_e32 v105, v168, v7
	ds_write_b32 v205, v104 offset:11872
	v_fmac_f32_e32 v5, v168, v6
	v_fma_f32 v104, -v169, v105, v4
	s_nop 0
	v_cvt_pk_bf16_f32 v4, v5, v105
	v_fmac_f32_e32 v104, v168, v5
	v_fmac_f32_e32 v108, v169, v5
	ds_write_b32 v205, v4 offset:11600
	v_fmac_f32_e32 v108, v168, v105
	s_nop 0
	v_cvt_pk_bf16_f32 v4, v104, v108
	ds_write_b32 v205, v4 offset:11328
	ds_read_b128 v[4:7], v175
	ds_read_b128 v[128:131], v175 offset:5120
	s_waitcnt lgkmcnt(1)
	v_fma_f32 v7, -v169, v108, v7
	s_waitcnt lgkmcnt(0)
	v_fma_f32 v105, v169, v104, v131
	v_fmac_f32_e32 v7, v168, v104
	v_fmac_f32_e32 v105, v168, v108
	v_fma_f32 v6, -v169, v105, v6
	v_cvt_pk_bf16_f32 v104, v7, v105
	v_fmac_f32_e32 v6, v168, v7
	v_fma_f32 v7, v169, v7, v130
	ds_write_b32 v205, v104 offset:11056
	v_fmac_f32_e32 v7, v168, v105
	v_fma_f32 v5, -v169, v7, v5
	v_fma_f32 v105, v169, v6, v129
	v_fmac_f32_e32 v105, v168, v7
	v_cvt_pk_bf16_f32 v104, v6, v7
	v_fmac_f32_e32 v5, v168, v6
	v_fma_f32 v129, -v169, v105, v4
	ds_write_b32 v205, v104 offset:10784
	s_nop 0
	v_cvt_pk_bf16_f32 v4, v5, v105
	v_fmac_f32_e32 v129, v168, v5
	v_fmac_f32_e32 v128, v169, v5
	ds_write_b32 v205, v4 offset:10512
	v_fmac_f32_e32 v128, v168, v105
	s_nop 0
	v_cvt_pk_bf16_f32 v4, v129, v128
	ds_write_b32 v205, v4 offset:10240
	s_waitcnt lgkmcnt(0)
	ds_read_b128 v[112:115], v204 offset:10240
	ds_read_b128 v[108:111], v204 offset:10304
	ds_read_b128 v[104:107], v204 offset:10368
	ds_read_b128 v[4:7], v204 offset:10432
	s_waitcnt lgkmcnt(0)
	ds_write_b128 v201, v[132:135]
	ds_write_b128 v201, v[136:139] offset:1280
	ds_write_b128 v201, v[140:143] offset:2560
	ds_write_b128 v202, v[148:151]
	ds_write_b128 v201, v[116:119] offset:5120
	ds_write_b128 v201, v[120:123] offset:6400
	ds_write_b128 v201, v[124:127] offset:7680
	ds_write_b128 v203, v[144:147]
	s_waitcnt lgkmcnt(0)
	ds_read_b128 v[0:3], v175 offset:48
	ds_read_b128 v[32:35], v175 offset:5168
	s_waitcnt lgkmcnt(13)
	v_mfma_f32_16x16x32_bf16 v[20:23], v[112:115], v[60:63], v[20:23]
	s_waitcnt lgkmcnt(1)
	v_fma_f32 v3, -v169, v128, v3
	s_waitcnt lgkmcnt(0)
	v_fma_f32 v35, v169, v129, v35
	v_fmac_f32_e32 v3, v168, v129
	v_fmac_f32_e32 v35, v168, v128
	v_fma_f32 v2, -v169, v35, v2
	v_cvt_pk_bf16_f32 v36, v3, v35
	v_fmac_f32_e32 v2, v168, v3
	v_fma_f32 v3, v169, v3, v34
	ds_write_b32 v205, v36 offset:14320
	v_fmac_f32_e32 v3, v168, v35
	v_fma_f32 v1, -v169, v3, v1
	v_fma_f32 v33, v169, v2, v33
	v_fmac_f32_e32 v33, v168, v3
	v_cvt_pk_bf16_f32 v34, v2, v3
	v_fmac_f32_e32 v1, v168, v2
	v_fma_f32 v38, -v169, v33, v0
	ds_write_b32 v205, v34 offset:14048
	v_mfma_f32_16x16x32_bf16 v[20:23], v[108:111], v[56:59], v[20:23]
	v_cvt_pk_bf16_f32 v0, v1, v33
	v_fmac_f32_e32 v38, v168, v1
	v_fmac_f32_e32 v32, v169, v1
	ds_write_b32 v205, v0 offset:13776
	v_fmac_f32_e32 v32, v168, v33
	v_mfma_f32_16x16x32_bf16 v[20:23], v[104:107], v[72:75], v[20:23]
	v_cvt_pk_bf16_f32 v0, v38, v32
	ds_write_b32 v205, v0 offset:13504
	ds_read_b128 v[0:3], v175 offset:32
	ds_read_b128 v[34:37], v175 offset:5152
	v_mfma_f32_16x16x32_bf16 v[4:7], v[4:7], v[76:79], v[20:23]
	s_waitcnt lgkmcnt(1)
	v_fma_f32 v3, -v169, v32, v3
	s_waitcnt lgkmcnt(0)
	v_fma_f32 v33, v169, v38, v37
	v_fmac_f32_e32 v3, v168, v38
	v_fmac_f32_e32 v33, v168, v32
	v_fma_f32 v2, -v169, v33, v2
	v_cvt_pk_bf16_f32 v32, v3, v33
	v_fmac_f32_e32 v2, v168, v3
	v_fma_f32 v3, v169, v3, v36
	ds_write_b32 v205, v32 offset:13232
	v_fmac_f32_e32 v3, v168, v33
	v_fma_f32 v1, -v169, v3, v1
	v_fma_f32 v33, v169, v2, v35
	v_cvt_pk_bf16_f32 v32, v2, v3
	v_fmac_f32_e32 v33, v168, v3
	ds_write_b32 v205, v32 offset:12960
	v_fmac_f32_e32 v1, v168, v2
	v_fma_f32 v32, -v169, v33, v0
	s_nop 0
	v_cvt_pk_bf16_f32 v0, v1, v33
	v_fmac_f32_e32 v32, v168, v1
	v_fmac_f32_e32 v34, v169, v1
	ds_write_b32 v205, v0 offset:12688
	v_fmac_f32_e32 v34, v168, v33
	s_nop 0
	v_cvt_pk_bf16_f32 v0, v32, v34
	ds_write_b32 v205, v0 offset:12416
	ds_read_b128 v[0:3], v175 offset:16
	ds_read_b128 v[36:39], v175 offset:5136
	s_waitcnt lgkmcnt(1)
	v_fma_f32 v3, -v169, v34, v3
	v_fmac_f32_e32 v3, v168, v32
	s_waitcnt lgkmcnt(0)
	v_fma_f32 v32, v169, v32, v39
	v_fmac_f32_e32 v32, v168, v34
	v_fma_f32 v2, -v169, v32, v2
	v_cvt_pk_bf16_f32 v33, v3, v32
	v_fmac_f32_e32 v2, v168, v3
	v_fma_f32 v3, v169, v3, v38
	v_fmac_f32_e32 v3, v168, v32
	ds_write_b32 v205, v33 offset:12144
	v_fma_f32 v1, -v169, v3, v1
	v_cvt_pk_bf16_f32 v32, v2, v3
	v_fmac_f32_e32 v1, v168, v2
	v_fma_f32 v2, v169, v2, v37
	v_fmac_f32_e32 v2, v168, v3
	v_fma_f32 v37, -v169, v2, v0
	ds_write_b32 v205, v32 offset:11872
	s_nop 0
	v_cvt_pk_bf16_f32 v3, v1, v2
	v_fmac_f32_e32 v37, v168, v1
	v_fmac_f32_e32 v36, v169, v1
	ds_write_b32 v205, v3 offset:11600
	v_fmac_f32_e32 v36, v168, v2
	s_nop 0
	v_cvt_pk_bf16_f32 v0, v37, v36
	ds_write_b32 v205, v0 offset:11328
	ds_read_b128 v[0:3], v175
	ds_read_b128 v[32:35], v175 offset:5120
	s_waitcnt lgkmcnt(1)
	v_fma_f32 v3, -v169, v36, v3
	s_waitcnt lgkmcnt(0)
	v_fma_f32 v35, v169, v37, v35
	v_fmac_f32_e32 v3, v168, v37
	v_fmac_f32_e32 v35, v168, v36
	v_fma_f32 v2, -v169, v35, v2
	v_cvt_pk_bf16_f32 v36, v3, v35
	v_fmac_f32_e32 v2, v168, v3
	v_fma_f32 v3, v169, v3, v34
	v_fmac_f32_e32 v3, v168, v35
	ds_write_b32 v205, v36 offset:11056
	v_fma_f32 v1, -v169, v3, v1
	v_cvt_pk_bf16_f32 v34, v2, v3
	v_fmac_f32_e32 v1, v168, v2
	v_fma_f32 v2, v169, v2, v33
	v_fmac_f32_e32 v2, v168, v3
	v_fma_f32 v0, -v169, v2, v0
	ds_write_b32 v205, v34 offset:10784
	s_nop 0
	v_cvt_pk_bf16_f32 v3, v1, v2
	v_fmac_f32_e32 v0, v168, v1
	ds_write_b32 v205, v3 offset:10512
	v_fmac_f32_e32 v32, v169, v1
	v_fmac_f32_e32 v32, v168, v2
	v_cvt_pk_bf16_f32 v0, v0, v32
	ds_write_b32 v205, v0 offset:10240
	s_waitcnt lgkmcnt(0)
	ds_read_b128 v[0:3], v204 offset:10240
	ds_read_b128 v[32:35], v204 offset:10304
	s_waitcnt lgkmcnt(1)
	v_mfma_f32_16x16x32_bf16 v[0:3], v[0:3], v[60:63], v[24:27]
	s_waitcnt lgkmcnt(0)
	v_mfma_f32_16x16x32_bf16 v[0:3], v[32:35], v[56:59], v[0:3]
	s_nop 0
	ds_read_b128 v[24:27], v204 offset:10368
	ds_read_b128 v[32:35], v204 offset:10432
	s_waitcnt lgkmcnt(0)
	s_waitcnt lgkmcnt(1)
	v_mfma_f32_16x16x32_bf16 v[24:27], v[24:27], v[72:75], v[0:3]
	s_nop 2
	v_or_b32_e32 v0, s7, v194
	v_or_b32_e32 v2, s2, v173
	v_ashrrev_i32_e32 v1, 31, v0
	v_lshlrev_b32_e32 v3, 2, v2
	v_lshlrev_b64 v[36:37], 11, v[0:1]
	v_lshlrev_b32_e32 v2, 1, v2
	v_or_b32_e32 v36, v36, v2
	v_lshl_add_u64 v[38:39], s[60:61], 0, v[36:37]
	s_nop 0
	global_load_dword v1, v3, s[46:47]
	s_waitcnt lgkmcnt(0)
	v_mfma_f32_16x16x32_bf16 v[24:27], v[32:35], v[76:79], v[24:27]
	v_or_b32_e32 v32, 1, v0
	v_ashrrev_i32_e32 v33, 31, v32
	v_lshlrev_b64 v[32:33], 11, v[32:33]
	v_lshl_add_u64 v[34:35], s[38:39], 0, v[36:37]
	v_or_b32_e32 v32, v32, v2
	v_lshl_add_u64 v[36:37], s[60:61], 0, v[32:33]
	v_lshl_add_u64 v[32:33], s[38:39], 0, v[32:33]
	v_or_b32_e32 v20, 17, v0
	v_ashrrev_i32_e32 v21, 31, v20
	v_lshlrev_b64 v[20:21], 11, v[20:21]
	v_or_b32_e32 v20, v20, v2
	s_waitcnt vmcnt(1)
	v_lshlrev_b32_e32 v3, 16, v214
	s_waitcnt vmcnt(0)
	v_fma_f32 v3, v1, v3, v24
	v_mul_f32_e32 v24, 0x3d372713, v3
	v_mul_f32_e32 v24, v3, v24
	v_fma_f32 v24, v3, v24, v3
	v_mul_f32_e32 v24, 0x3f4c422a, v24
	v_mul_f32_e32 v24, 0x4038aa3b, v24
	v_exp_f32_e32 v24, v24
	v_mul_f32_e32 v3, 0.5, v3
	v_add_f32_e32 v24, 1.0, v24
	v_rcp_f32_e32 v24, v24
	s_nop 0
	v_fma_f32 v24, v24, -2.0, 1.0
	v_add_f32_e32 v24, 1.0, v24
	v_mul_f32_e32 v3, v3, v24
	v_cvt_pk_bf16_f32 v3, v3, v177
	global_store_short v[34:35], v3, off
	v_or_b32_e32 v24, 2, v0
	v_lshlrev_b32_e32 v3, 16, v215
	v_fma_f32 v3, v1, v3, v25
	v_mul_f32_e32 v25, 0x3d372713, v3
	v_mul_f32_e32 v25, v3, v25
	v_fma_f32 v25, v3, v25, v3
	v_mul_f32_e32 v25, 0x3f4c422a, v25
	v_mul_f32_e32 v25, 0x4038aa3b, v25
	v_exp_f32_e32 v34, v25
	v_ashrrev_i32_e32 v25, 31, v24
	v_lshlrev_b64 v[24:25], 11, v[24:25]
	v_mul_f32_e32 v3, 0.5, v3
	v_add_f32_e32 v34, 1.0, v34
	v_rcp_f32_e32 v36, v34
	v_or_b32_e32 v24, v24, v2
	v_lshl_add_u64 v[34:35], s[60:61], 0, v[24:25]
	v_lshl_add_u64 v[24:25], s[38:39], 0, v[24:25]
	v_fma_f32 v36, v36, -2.0, 1.0
	v_add_f32_e32 v36, 1.0, v36
	v_mul_f32_e32 v3, v3, v36
	v_cvt_pk_bf16_f32 v3, v3, v177
	global_store_short v[32:33], v3, off
	v_or_b32_e32 v32, 3, v0
	v_ashrrev_i32_e32 v33, 31, v32
	v_lshlrev_b64 v[32:33], 11, v[32:33]
	v_or_b32_e32 v32, v32, v2
	v_lshl_add_u64 v[34:35], s[60:61], 0, v[32:33]
	v_lshl_add_u64 v[32:33], s[38:39], 0, v[32:33]
	v_lshlrev_b32_e32 v3, 16, v216
	v_fma_f32 v3, v1, v3, v26
	v_mul_f32_e32 v26, 0x3d372713, v3
	v_mul_f32_e32 v26, v3, v26
	v_fma_f32 v26, v3, v26, v3
	v_mul_f32_e32 v26, 0x3f4c422a, v26
	v_mul_f32_e32 v26, 0x4038aa3b, v26
	v_exp_f32_e32 v26, v26
	v_mul_f32_e32 v3, 0.5, v3
	v_add_f32_e32 v26, 1.0, v26
	v_rcp_f32_e32 v26, v26
	s_nop 0
	v_fma_f32 v26, v26, -2.0, 1.0
	v_add_f32_e32 v26, 1.0, v26
	v_mul_f32_e32 v3, v3, v26
	v_cvt_pk_bf16_f32 v3, v3, v177
	global_store_short v[24:25], v3, off
	v_or_b32_e32 v24, 16, v0
	v_ashrrev_i32_e32 v25, 31, v24
	v_lshlrev_b64 v[24:25], 11, v[24:25]
	v_or_b32_e32 v24, v24, v2
	v_lshl_add_u64 v[34:35], s[60:61], 0, v[24:25]
	v_lshl_add_u64 v[22:23], s[38:39], 0, v[24:25]
	v_lshl_add_u64 v[24:25], s[60:61], 0, v[20:21]
	v_lshl_add_u64 v[20:21], s[38:39], 0, v[20:21]
	v_lshlrev_b32_e32 v3, 16, v217
	v_fmac_f32_e32 v27, v1, v3
	v_mul_f32_e32 v3, 0x3d372713, v27
	v_mul_f32_e32 v3, v27, v3
	v_fma_f32 v3, v27, v3, v27
	v_mul_f32_e32 v3, 0x3f4c422a, v3
	v_mul_f32_e32 v3, 0x4038aa3b, v3
	v_exp_f32_e32 v3, v3
	v_mul_f32_e32 v26, 0.5, v27
	v_add_f32_e32 v3, 1.0, v3
	v_rcp_f32_e32 v3, v3
	s_nop 0
	v_fma_f32 v3, v3, -2.0, 1.0
	v_add_f32_e32 v3, 1.0, v3
	v_mul_f32_e32 v3, v26, v3
	v_cvt_pk_bf16_f32 v3, v3, v177
	global_store_short v[32:33], v3, off
	v_lshlrev_b32_e32 v3, 16, v218
	v_fma_f32 v3, v1, v3, v4
	v_mul_f32_e32 v4, 0x3d372713, v3
	v_mul_f32_e32 v4, v3, v4
	v_fma_f32 v4, v3, v4, v3
	v_mul_f32_e32 v4, 0x3f4c422a, v4
	v_mul_f32_e32 v4, 0x4038aa3b, v4
	v_exp_f32_e32 v4, v4
	v_mul_f32_e32 v3, 0.5, v3
	v_add_f32_e32 v4, 1.0, v4
	v_rcp_f32_e32 v4, v4
	s_nop 0
	v_fma_f32 v4, v4, -2.0, 1.0
	v_add_f32_e32 v4, 1.0, v4
	v_mul_f32_e32 v3, v3, v4
	v_cvt_pk_bf16_f32 v3, v3, v177
	global_store_short v[22:23], v3, off
	v_or_b32_e32 v4, 18, v0
	v_lshlrev_b32_e32 v3, 16, v219
	v_fma_f32 v3, v1, v3, v5
	v_mul_f32_e32 v5, 0x3d372713, v3
	v_mul_f32_e32 v5, v3, v5
	v_fma_f32 v5, v3, v5, v3
	v_mul_f32_e32 v5, 0x3f4c422a, v5
	v_mul_f32_e32 v5, 0x4038aa3b, v5
	v_exp_f32_e32 v22, v5
	v_ashrrev_i32_e32 v5, 31, v4
	v_lshlrev_b64 v[4:5], 11, v[4:5]
	v_mul_f32_e32 v3, 0.5, v3
	v_add_f32_e32 v22, 1.0, v22
	v_rcp_f32_e32 v24, v22
	v_or_b32_e32 v4, v4, v2
	v_lshl_add_u64 v[22:23], s[60:61], 0, v[4:5]
	v_lshl_add_u64 v[4:5], s[38:39], 0, v[4:5]
	v_fma_f32 v24, v24, -2.0, 1.0
	v_add_f32_e32 v24, 1.0, v24
	v_mul_f32_e32 v3, v3, v24
	v_cvt_pk_bf16_f32 v3, v3, v177
	global_store_short v[20:21], v3, off
	v_or_b32_e32 v20, 19, v0
	v_ashrrev_i32_e32 v21, 31, v20
	v_lshlrev_b64 v[24:25], 11, v[20:21]
	v_or_b32_e32 v24, v24, v2
	v_lshl_add_u64 v[20:21], s[60:61], 0, v[24:25]
	v_lshlrev_b32_e32 v3, 16, v220
	v_fma_f32 v3, v1, v3, v6
	v_mul_f32_e32 v6, 0x3d372713, v3
	v_mul_f32_e32 v6, v3, v6
	v_fma_f32 v6, v3, v6, v3
	v_mul_f32_e32 v6, 0x3f4c422a, v6
	v_mul_f32_e32 v6, 0x4038aa3b, v6
	v_exp_f32_e32 v6, v6
	v_mul_f32_e32 v3, 0.5, v3
	v_add_f32_e32 v6, 1.0, v6
	v_rcp_f32_e32 v6, v6
	s_nop 0
	v_fma_f32 v6, v6, -2.0, 1.0
	v_add_f32_e32 v6, 1.0, v6
	v_mul_f32_e32 v3, v3, v6
	v_cvt_pk_bf16_f32 v3, v3, v177
	global_store_short v[4:5], v3, off
	v_or_b32_e32 v4, 32, v0
	v_ashrrev_i32_e32 v5, 31, v4
	v_lshlrev_b64 v[26:27], 11, v[4:5]
	v_or_b32_e32 v26, v26, v2
	v_lshl_add_u64 v[4:5], s[38:39], 0, v[24:25]
	v_lshl_add_u64 v[24:25], s[60:61], 0, v[26:27]
	v_mfma_f32_16x16x32_bf16 v[20:23], v[100:103], v[60:63], v[28:31]
	v_lshlrev_b32_e32 v3, 16, v221
	v_fmac_f32_e32 v7, v1, v3
	v_mul_f32_e32 v3, 0x3d372713, v7
	v_mul_f32_e32 v3, v7, v3
	v_fma_f32 v3, v7, v3, v7
	v_mul_f32_e32 v3, 0x3f4c422a, v3
	v_mul_f32_e32 v3, 0x4038aa3b, v3
	v_exp_f32_e32 v3, v3
	v_mul_f32_e32 v6, 0.5, v7
	v_mfma_f32_16x16x32_bf16 v[20:23], v[96:99], v[56:59], v[20:23]
	v_add_f32_e32 v3, 1.0, v3
	v_rcp_f32_e32 v3, v3
	v_mfma_f32_16x16x32_bf16 v[20:23], v[92:95], v[72:75], v[20:23]
	v_fma_f32 v3, v3, -2.0, 1.0
	v_add_f32_e32 v3, 1.0, v3
	v_mul_f32_e32 v3, v6, v3
	v_cvt_pk_bf16_f32 v3, v3, v177
	global_store_short v[4:5], v3, off
	v_mfma_f32_16x16x32_bf16 v[4:7], v[8:11], v[76:79], v[20:23]
	v_or_b32_e32 v8, 33, v0
	v_ashrrev_i32_e32 v9, 31, v8
	v_lshlrev_b64 v[8:9], 11, v[8:9]
	v_or_b32_e32 v8, v8, v2
	v_lshl_add_u64 v[10:11], s[38:39], 0, v[26:27]
	v_lshl_add_u64 v[20:21], s[60:61], 0, v[8:9]
	v_lshl_add_u64 v[8:9], s[38:39], 0, v[8:9]
	v_lshlrev_b32_e32 v3, 16, v222
	v_fma_f32 v3, v1, v3, v4
	v_mul_f32_e32 v4, 0x3d372713, v3
	v_mul_f32_e32 v4, v3, v4
	v_fma_f32 v4, v3, v4, v3
	v_mul_f32_e32 v4, 0x3f4c422a, v4
	v_mul_f32_e32 v4, 0x4038aa3b, v4
	v_exp_f32_e32 v4, v4
	v_mul_f32_e32 v3, 0.5, v3
	v_add_f32_e32 v4, 1.0, v4
	v_rcp_f32_e32 v4, v4
	s_nop 0
	v_fma_f32 v4, v4, -2.0, 1.0
	v_add_f32_e32 v4, 1.0, v4
	v_mul_f32_e32 v3, v3, v4
	v_cvt_pk_bf16_f32 v3, v3, v177
	global_store_short v[10:11], v3, off
	v_or_b32_e32 v4, 34, v0
	v_lshlrev_b32_e32 v3, 16, v223
	v_fma_f32 v3, v1, v3, v5
	v_mul_f32_e32 v5, 0x3d372713, v3
	v_mul_f32_e32 v5, v3, v5
	v_fma_f32 v5, v3, v5, v3
	v_mul_f32_e32 v5, 0x3f4c422a, v5
	v_mul_f32_e32 v5, 0x4038aa3b, v5
	v_exp_f32_e32 v10, v5
	v_ashrrev_i32_e32 v5, 31, v4
	v_lshlrev_b64 v[4:5], 11, v[4:5]
	v_mul_f32_e32 v3, 0.5, v3
	v_add_f32_e32 v10, 1.0, v10
	v_rcp_f32_e32 v20, v10
	v_or_b32_e32 v4, v4, v2
	v_lshl_add_u64 v[10:11], s[60:61], 0, v[4:5]
	v_lshl_add_u64 v[4:5], s[38:39], 0, v[4:5]
	v_fma_f32 v20, v20, -2.0, 1.0
	v_add_f32_e32 v20, 1.0, v20
	v_mul_f32_e32 v3, v3, v20
	v_cvt_pk_bf16_f32 v3, v3, v177
	global_store_short v[8:9], v3, off
	v_or_b32_e32 v8, 35, v0
	v_ashrrev_i32_e32 v9, 31, v8
	v_lshlrev_b64 v[20:21], 11, v[8:9]
	v_or_b32_e32 v20, v20, v2
	v_lshl_add_u64 v[8:9], s[60:61], 0, v[20:21]
	v_lshlrev_b32_e32 v3, 16, v224
	v_fma_f32 v3, v1, v3, v6
	v_mul_f32_e32 v6, 0x3d372713, v3
	v_mul_f32_e32 v6, v3, v6
	v_fma_f32 v6, v3, v6, v3
	v_mul_f32_e32 v6, 0x3f4c422a, v6
	v_mul_f32_e32 v6, 0x4038aa3b, v6
	v_exp_f32_e32 v6, v6
	v_mul_f32_e32 v3, 0.5, v3
	v_add_f32_e32 v6, 1.0, v6
	v_rcp_f32_e32 v6, v6
	s_nop 0
	v_fma_f32 v6, v6, -2.0, 1.0
	v_add_f32_e32 v6, 1.0, v6
	v_mul_f32_e32 v3, v3, v6
	v_cvt_pk_bf16_f32 v3, v3, v177
	global_store_short v[4:5], v3, off
	v_or_b32_e32 v4, 48, v0
	v_ashrrev_i32_e32 v5, 31, v4
	v_lshlrev_b64 v[22:23], 11, v[4:5]
	v_or_b32_e32 v22, v22, v2
	v_lshl_add_u64 v[4:5], s[38:39], 0, v[20:21]
	v_mfma_f32_16x16x32_bf16 v[8:11], v[88:91], v[60:63], v[16:19]
	v_lshlrev_b32_e32 v3, 16, v225
	v_fmac_f32_e32 v7, v1, v3
	v_mul_f32_e32 v3, 0x3d372713, v7
	v_mul_f32_e32 v3, v7, v3
	v_fma_f32 v3, v7, v3, v7
	v_mul_f32_e32 v3, 0x3f4c422a, v3
	v_mul_f32_e32 v3, 0x4038aa3b, v3
	v_exp_f32_e32 v3, v3
	v_mul_f32_e32 v6, 0.5, v7
	v_lshl_add_u64 v[16:17], s[60:61], 0, v[22:23]
	v_mfma_f32_16x16x32_bf16 v[8:11], v[84:87], v[56:59], v[8:11]
	v_add_f32_e32 v3, 1.0, v3
	v_rcp_f32_e32 v3, v3
	v_mfma_f32_16x16x32_bf16 v[8:11], v[80:83], v[72:75], v[8:11]
	v_fma_f32 v3, v3, -2.0, 1.0
	v_add_f32_e32 v3, 1.0, v3
	v_mul_f32_e32 v3, v6, v3
	v_cvt_pk_bf16_f32 v3, v3, v177
	global_store_short v[4:5], v3, off
	v_mfma_f32_16x16x32_bf16 v[4:7], v[12:15], v[76:79], v[8:11]
	v_lshlrev_b32_e32 v3, 16, v226
	s_nop 5
	v_fma_f32 v3, v1, v3, v4
	v_mul_f32_e32 v4, 0x3d372713, v3
	v_mul_f32_e32 v4, v3, v4
	v_fma_f32 v4, v3, v4, v3
	v_mul_f32_e32 v4, 0x3f4c422a, v4
	v_mul_f32_e32 v4, 0x4038aa3b, v4
	v_exp_f32_e32 v4, v4
	v_or_b32_e32 v8, 49, v0
	v_ashrrev_i32_e32 v9, 31, v8
	v_lshlrev_b64 v[8:9], 11, v[8:9]
	v_add_f32_e32 v4, 1.0, v4
	v_rcp_f32_e32 v4, v4
	v_mul_f32_e32 v3, 0.5, v3
	v_or_b32_e32 v8, v8, v2
	v_lshl_add_u64 v[10:11], s[38:39], 0, v[22:23]
	v_fma_f32 v4, v4, -2.0, 1.0
	v_add_f32_e32 v4, 1.0, v4
	v_mul_f32_e32 v3, v3, v4
	v_lshl_add_u64 v[12:13], s[60:61], 0, v[8:9]
	v_cvt_pk_bf16_f32 v3, v3, v177
	global_store_short v[10:11], v3, off
	v_or_b32_e32 v4, 50, v0
	v_lshl_add_u64 v[8:9], s[38:39], 0, v[8:9]
	v_lshlrev_b32_e32 v3, 16, v227
	v_fma_f32 v3, v1, v3, v5
	v_mul_f32_e32 v5, 0x3d372713, v3
	v_mul_f32_e32 v5, v3, v5
	v_fma_f32 v5, v3, v5, v3
	v_mul_f32_e32 v5, 0x3f4c422a, v5
	v_mul_f32_e32 v5, 0x4038aa3b, v5
	v_exp_f32_e32 v10, v5
	v_ashrrev_i32_e32 v5, 31, v4
	v_lshlrev_b64 v[4:5], 11, v[4:5]
	v_mul_f32_e32 v3, 0.5, v3
	v_add_f32_e32 v10, 1.0, v10
	v_rcp_f32_e32 v12, v10
	v_or_b32_e32 v4, v4, v2
	v_lshl_add_u64 v[10:11], s[60:61], 0, v[4:5]
	v_fma_f32 v12, v12, -2.0, 1.0
	v_add_f32_e32 v12, 1.0, v12
	v_mul_f32_e32 v3, v3, v12
	v_cvt_pk_bf16_f32 v3, v3, v177
	global_store_short v[8:9], v3, off
	v_or_b32_e32 v8, 51, v0
	v_ashrrev_i32_e32 v9, 31, v8
	v_lshlrev_b64 v[8:9], 11, v[8:9]
	v_or_b32_e32 v8, v8, v2
	v_lshlrev_b32_e32 v0, 16, v228
	v_fma_f32 v0, v1, v0, v6
	v_mul_f32_e32 v3, 0x3d372713, v0
	v_mul_f32_e32 v3, v0, v3
	v_fma_f32 v3, v0, v3, v0
	v_mul_f32_e32 v3, 0x3f4c422a, v3
	v_mul_f32_e32 v3, 0x4038aa3b, v3
	v_exp_f32_e32 v3, v3
	v_mul_f32_e32 v0, 0.5, v0
	v_add_f32_e32 v2, 1.0, v3
	v_rcp_f32_e32 v6, v2
	v_lshl_add_u64 v[2:3], s[38:39], 0, v[4:5]
	v_lshl_add_u64 v[4:5], s[60:61], 0, v[8:9]
	v_fma_f32 v6, v6, -2.0, 1.0
	v_add_f32_e32 v6, 1.0, v6
	v_mul_f32_e32 v0, v0, v6
	v_cvt_pk_bf16_f32 v0, v0, v177
	global_store_short v[2:3], v0, off
	v_lshlrev_b32_e32 v0, 16, v229
	v_fmac_f32_e32 v7, v1, v0
	v_mul_f32_e32 v0, 0x3d372713, v7
	v_mul_f32_e32 v0, v7, v0
	v_fma_f32 v0, v7, v0, v7
	v_mul_f32_e32 v0, 0x3f4c422a, v0
	v_mul_f32_e32 v0, 0x4038aa3b, v0
	v_exp_f32_e32 v0, v0
	v_mul_f32_e32 v3, 0.5, v7
	v_add_f32_e32 v0, 1.0, v0
	v_rcp_f32_e32 v2, v0
	v_lshl_add_u64 v[0:1], s[38:39], 0, v[8:9]
	v_fma_f32 v2, v2, -2.0, 1.0
	v_add_f32_e32 v2, 1.0, v2
	v_mul_f32_e32 v2, v3, v2
	v_cvt_pk_bf16_f32 v2, v2, v177
	global_store_short v[0:1], v2, off
	s_cbranch_scc1 .LBB0_1562

.LBB0_1546:
	s_or_b64 exec, exec, s[4:5]
	v_lshl_or_b32 v176, s8, 12, v200
	v_lshl_add_u64 v[238:239], v[186:187], 0, v[176:177]
	v_lshl_add_u64 v[164:165], v[188:189], 0, v[176:177]
	global_load_dwordx4 v[214:217], v[238:239], off
	global_load_dwordx4 v[218:221], v[164:165], off
	global_load_dwordx4 v[222:225], v[238:239], off offset:64
	global_load_dwordx4 v[226:229], v[164:165], off offset:64
	global_load_dwordx4 v[230:233], v[238:239], off offset:128
	global_load_dwordx4 v[234:237], v[164:165], off offset:128
	global_load_dwordx4 v[92:95], v[238:239], off offset:192
	global_load_dwordx4 v[168:171], v[164:165], off offset:192
	s_ashr_i32 s9, s6, 5
	s_and_b32 s4, s9, -2
	s_lshl_b32 s2, s2, 3
	s_ashr_i32 s5, s4, 31
	v_lshl_add_u64 v[192:193], v[184:185], 0, s[2:3]
	s_lshl_b64 s[4:5], s[4:5], 15
	v_lshl_add_u64 v[206:207], v[192:193], 0, s[4:5]
	global_load_dwordx2 v[206:207], v[206:207], off
	s_waitcnt vmcnt(7)
	v_xor_b32_e32 v218, 0x80000000, v218
	v_xor_b32_e32 v219, 0x80000000, v219
	v_xor_b32_e32 v220, 0x80000000, v220
	v_xor_b32_e32 v221, 0x80000000, v221
	v_cvt_pk_bf16_f32 v52, v214, v218
	v_cvt_pk_bf16_f32 v53, v215, v219
	v_cvt_pk_bf16_f32 v54, v216, v220
	v_cvt_pk_bf16_f32 v55, v217, v221
	s_waitcnt vmcnt(5)
	v_xor_b32_e32 v226, 0x80000000, v226
	v_xor_b32_e32 v227, 0x80000000, v227
	v_xor_b32_e32 v228, 0x80000000, v228
	v_xor_b32_e32 v229, 0x80000000, v229
	v_cvt_pk_bf16_f32 v56, v222, v226
	v_cvt_pk_bf16_f32 v57, v223, v227
	v_cvt_pk_bf16_f32 v58, v224, v228
	v_cvt_pk_bf16_f32 v59, v225, v229
	s_waitcnt vmcnt(3)
	v_xor_b32_e32 v234, 0x80000000, v234
	v_xor_b32_e32 v235, 0x80000000, v235
	v_xor_b32_e32 v236, 0x80000000, v236
	v_xor_b32_e32 v237, 0x80000000, v237
	v_cvt_pk_bf16_f32 v60, v230, v234
	v_cvt_pk_bf16_f32 v61, v231, v235
	v_cvt_pk_bf16_f32 v62, v232, v236
	v_cvt_pk_bf16_f32 v63, v233, v237
	s_waitcnt vmcnt(1)
	v_xor_b32_e32 v168, 0x80000000, v168
	v_xor_b32_e32 v169, 0x80000000, v169
	v_xor_b32_e32 v170, 0x80000000, v170
	v_xor_b32_e32 v171, 0x80000000, v171
	v_cvt_pk_bf16_f32 v92, v92, v168
	v_cvt_pk_bf16_f32 v93, v93, v169
	v_cvt_pk_bf16_f32 v94, v94, v170
	v_cvt_pk_bf16_f32 v95, v95, v171
	v_mfma_f32_16x16x32_bf16 v[24:27], v[0:3], v[20:23], 0
	s_or_b32 s10, s8, 64
	v_lshl_or_b32 v176, s10, 12, v195
	v_mfma_f32_16x16x32_bf16 v[64:67], v[0:3], v[16:19], 0
	v_mfma_f32_16x16x32_bf16 v[68:71], v[0:3], v[28:31], 0
	v_mfma_f32_16x16x32_bf16 v[72:75], v[0:3], v[32:35], 0
	v_mfma_f32_16x16x32_bf16 v[76:79], v[0:3], v[36:39], 0
	v_mfma_f32_16x16x32_bf16 v[80:83], v[0:3], v[40:43], 0
	v_mfma_f32_16x16x32_bf16 v[84:87], v[0:3], v[44:47], 0
	v_mfma_f32_16x16x32_bf16 v[88:91], v[0:3], v[48:51], 0
	ds_write_b128 v201, v[24:27]
	ds_write_b128 v201, v[64:67] offset:1280
	s_nop 0
	ds_write_b128 v201, v[68:71] offset:2560
	ds_write_b128 v202, v[72:75]
	ds_write_b128 v201, v[76:79] offset:5120
	ds_write_b128 v201, v[80:83] offset:6400
	ds_write_b128 v201, v[84:87] offset:7680
	ds_write_b128 v203, v[88:91]
	s_waitcnt lgkmcnt(0)
	ds_read_b128 v[24:27], v175
	ds_read_b128 v[70:73], v175 offset:5120
	v_mfma_f32_16x16x32_bf16 v[96:99], v[4:7], v[20:23], 0
	s_waitcnt vmcnt(0) lgkmcnt(1)
	v_fma_f32 v24, -v191, v207, v24
	s_waitcnt lgkmcnt(0)
	v_fma_f32 v68, v191, v206, v70
	v_fmac_f32_e32 v24, v190, v206
	v_fmac_f32_e32 v68, v190, v207
	v_fma_f32 v25, -v191, v68, v25
	v_cvt_pk_bf16_f32 v69, v24, v68
	v_fmac_f32_e32 v25, v190, v24
	v_fma_f32 v24, v191, v24, v71
	ds_write_b32 v205, v69 offset:10240
	v_fmac_f32_e32 v24, v190, v68
	v_fma_f32 v26, -v191, v24, v26
	v_fma_f32 v69, v191, v25, v72
	v_fmac_f32_e32 v69, v190, v24
	v_cvt_pk_bf16_f32 v68, v25, v24
	v_fmac_f32_e32 v26, v190, v25
	v_fma_f32 v72, -v191, v69, v27
	ds_write_b32 v205, v68 offset:10512
	v_mfma_f32_16x16x32_bf16 v[100:103], v[4:7], v[16:19], 0
	v_cvt_pk_bf16_f32 v24, v26, v69
	v_fmac_f32_e32 v72, v190, v26
	v_fmac_f32_e32 v73, v191, v26
	ds_write_b32 v205, v24 offset:10784
	v_fmac_f32_e32 v73, v190, v69
	v_mfma_f32_16x16x32_bf16 v[104:107], v[4:7], v[28:31], 0
	v_cvt_pk_bf16_f32 v24, v72, v73
	ds_write_b32 v205, v24 offset:11056
	ds_read_b128 v[24:27], v175 offset:16
	ds_read_b128 v[74:77], v175 offset:5136
	v_mfma_f32_16x16x32_bf16 v[108:111], v[4:7], v[32:35], 0
	s_waitcnt lgkmcnt(1)
	v_fma_f32 v24, -v191, v73, v24
	s_waitcnt lgkmcnt(0)
	v_fma_f32 v74, v191, v72, v74
	v_fmac_f32_e32 v24, v190, v72
	v_fmac_f32_e32 v74, v190, v73
	v_fma_f32 v25, -v191, v74, v25
	v_cvt_pk_bf16_f32 v72, v24, v74
	v_fmac_f32_e32 v25, v190, v24
	v_fma_f32 v24, v191, v24, v75
	ds_write_b32 v205, v72 offset:11328
	v_fmac_f32_e32 v24, v190, v74
	v_fma_f32 v26, -v191, v24, v26
	v_fma_f32 v73, v191, v25, v76
	v_fmac_f32_e32 v73, v190, v24
	v_cvt_pk_bf16_f32 v72, v25, v24
	v_fmac_f32_e32 v26, v190, v25
	v_fma_f32 v76, -v191, v73, v27
	ds_write_b32 v205, v72 offset:11600
	v_mfma_f32_16x16x32_bf16 v[112:115], v[4:7], v[36:39], 0
	v_cvt_pk_bf16_f32 v24, v26, v73
	v_fmac_f32_e32 v76, v190, v26
	v_fmac_f32_e32 v77, v191, v26
	ds_write_b32 v205, v24 offset:11872
	v_fmac_f32_e32 v77, v190, v73
	v_mfma_f32_16x16x32_bf16 v[116:119], v[4:7], v[40:43], 0
	v_cvt_pk_bf16_f32 v24, v76, v77
	ds_write_b32 v205, v24 offset:12144
	ds_read_b128 v[24:27], v175 offset:32
	ds_read_b128 v[78:81], v175 offset:5152
	v_mfma_f32_16x16x32_bf16 v[120:123], v[4:7], v[44:47], 0
	s_waitcnt lgkmcnt(1)
	v_fma_f32 v24, -v191, v77, v24
	s_waitcnt lgkmcnt(0)
	v_fma_f32 v78, v191, v76, v78
	v_fmac_f32_e32 v24, v190, v76
	v_fmac_f32_e32 v78, v190, v77
	v_fma_f32 v25, -v191, v78, v25
	v_cvt_pk_bf16_f32 v76, v24, v78
	v_fmac_f32_e32 v25, v190, v24
	v_fma_f32 v24, v191, v24, v79
	ds_write_b32 v205, v76 offset:12416
	v_fmac_f32_e32 v24, v190, v78
	v_fma_f32 v26, -v191, v24, v26
	v_fma_f32 v77, v191, v25, v80
	v_fmac_f32_e32 v77, v190, v24
	v_cvt_pk_bf16_f32 v76, v25, v24
	v_fmac_f32_e32 v26, v190, v25
	v_fma_f32 v80, -v191, v77, v27
	ds_write_b32 v205, v76 offset:12688
	v_mfma_f32_16x16x32_bf16 v[124:127], v[4:7], v[48:51], 0
	v_cvt_pk_bf16_f32 v24, v26, v77
	v_fmac_f32_e32 v80, v190, v26
	v_fmac_f32_e32 v81, v191, v26
	ds_write_b32 v205, v24 offset:12960
	v_fmac_f32_e32 v81, v190, v77
	v_mfma_f32_16x16x32_bf16 v[128:131], v[8:11], v[20:23], 0
	v_cvt_pk_bf16_f32 v24, v80, v81
	ds_write_b32 v205, v24 offset:13232
	ds_read_b128 v[24:27], v175 offset:48
	ds_read_b128 v[82:85], v175 offset:5168
	v_mfma_f32_16x16x32_bf16 v[132:135], v[8:11], v[16:19], 0
	s_waitcnt lgkmcnt(1)
	v_fma_f32 v24, -v191, v81, v24
	s_waitcnt lgkmcnt(0)
	v_fma_f32 v82, v191, v80, v82
	v_fmac_f32_e32 v24, v190, v80
	v_fmac_f32_e32 v82, v190, v81
	v_fma_f32 v25, -v191, v82, v25
	v_cvt_pk_bf16_f32 v80, v24, v82
	v_fmac_f32_e32 v25, v190, v24
	v_fma_f32 v24, v191, v24, v83
	ds_write_b32 v205, v80 offset:13504
	v_fmac_f32_e32 v24, v190, v82
	v_fma_f32 v26, -v191, v24, v26
	v_fma_f32 v81, v191, v25, v84
	v_fmac_f32_e32 v81, v190, v24
	v_cvt_pk_bf16_f32 v80, v25, v24
	v_fmac_f32_e32 v26, v190, v25
	v_fma_f32 v84, -v191, v81, v27
	ds_write_b32 v205, v80 offset:13776
	v_mfma_f32_16x16x32_bf16 v[136:139], v[8:11], v[28:31], 0
	v_cvt_pk_bf16_f32 v24, v26, v81
	v_fmac_f32_e32 v84, v190, v26
	v_fmac_f32_e32 v85, v191, v26
	ds_write_b32 v205, v24 offset:14048
	v_fmac_f32_e32 v85, v190, v81
	v_mfma_f32_16x16x32_bf16 v[140:143], v[8:11], v[32:35], 0
	v_cvt_pk_bf16_f32 v24, v84, v85
	ds_write_b32 v205, v24 offset:14320
	s_waitcnt lgkmcnt(0)
	ds_read_b128 v[24:27], v204 offset:10240
	ds_read_b128 v[86:89], v204 offset:10304
	ds_read_b128 v[206:209], v204 offset:10368
	ds_read_b128 v[210:213], v204 offset:10432
	s_waitcnt lgkmcnt(0)
	ds_write_b128 v201, v[96:99]
	ds_write_b128 v201, v[100:103] offset:1280
	ds_write_b128 v201, v[104:107] offset:2560
	ds_write_b128 v202, v[108:111]
	ds_write_b128 v201, v[112:115] offset:5120
	ds_write_b128 v201, v[116:119] offset:6400
	ds_write_b128 v201, v[120:123] offset:7680
	ds_write_b128 v203, v[124:127]
	s_waitcnt lgkmcnt(0)
	ds_read_b128 v[96:99], v175
	ds_read_b128 v[100:103], v175 offset:5120
	s_waitcnt lgkmcnt(13)
	v_mfma_f32_16x16x32_bf16 v[24:27], v[24:27], v[52:55], 0
	s_waitcnt lgkmcnt(1)
	v_fma_f32 v90, -v191, v85, v96
	s_waitcnt lgkmcnt(0)
	v_fma_f32 v91, v191, v84, v100
	v_fmac_f32_e32 v90, v190, v84
	v_fmac_f32_e32 v91, v190, v85
	v_fma_f32 v84, -v191, v91, v97
	v_cvt_pk_bf16_f32 v85, v90, v91
	v_fmac_f32_e32 v84, v190, v90
	v_fma_f32 v90, v191, v90, v101
	ds_write_b32 v205, v85 offset:10240
	v_fmac_f32_e32 v90, v190, v91
	v_fma_f32 v91, -v191, v90, v98
	v_fma_f32 v96, v191, v84, v102
	v_fmac_f32_e32 v96, v190, v90
	v_cvt_pk_bf16_f32 v85, v84, v90
	v_fmac_f32_e32 v91, v190, v84
	v_fma_f32 v84, -v191, v96, v99
	ds_write_b32 v205, v85 offset:10512
	v_mfma_f32_16x16x32_bf16 v[24:27], v[86:89], v[56:59], v[24:27]
	v_cvt_pk_bf16_f32 v85, v91, v96
	v_fmac_f32_e32 v84, v190, v91
	v_fmac_f32_e32 v103, v191, v91
	ds_write_b32 v205, v85 offset:10784
	v_fmac_f32_e32 v103, v190, v96
	v_mfma_f32_16x16x32_bf16 v[144:147], v[8:11], v[36:39], 0
	v_cvt_pk_bf16_f32 v85, v84, v103
	ds_write_b32 v205, v85 offset:11056
	ds_read_b128 v[96:99], v175 offset:16
	ds_read_b128 v[104:107], v175 offset:5136
	v_mfma_f32_16x16x32_bf16 v[148:151], v[8:11], v[40:43], 0
	s_waitcnt lgkmcnt(1)
	v_fma_f32 v85, -v191, v103, v96
	s_waitcnt lgkmcnt(0)
	v_fma_f32 v90, v191, v84, v104
	v_fmac_f32_e32 v85, v190, v84
	v_fmac_f32_e32 v90, v190, v103
	v_fma_f32 v84, -v191, v90, v97
	v_cvt_pk_bf16_f32 v91, v85, v90
	v_fmac_f32_e32 v84, v190, v85
	v_fma_f32 v85, v191, v85, v105
	ds_write_b32 v205, v91 offset:11328
	v_fmac_f32_e32 v85, v190, v90
	v_fma_f32 v91, -v191, v85, v98
	v_fma_f32 v96, v191, v84, v106
	v_fmac_f32_e32 v96, v190, v85
	v_cvt_pk_bf16_f32 v90, v84, v85
	v_fmac_f32_e32 v91, v190, v84
	v_fma_f32 v84, -v191, v96, v99
	ds_write_b32 v205, v90 offset:11600
	v_mfma_f32_16x16x32_bf16 v[152:155], v[8:11], v[44:47], 0
	v_cvt_pk_bf16_f32 v85, v91, v96
	v_fmac_f32_e32 v84, v190, v91
	v_fmac_f32_e32 v107, v191, v91
	ds_write_b32 v205, v85 offset:11872
	v_fmac_f32_e32 v107, v190, v96
	v_mfma_f32_16x16x32_bf16 v[156:159], v[8:11], v[48:51], 0
	v_cvt_pk_bf16_f32 v85, v84, v107
	ds_write_b32 v205, v85 offset:12144
	ds_read_b128 v[96:99], v175 offset:32
	ds_read_b128 v[100:103], v175 offset:5152
	v_mfma_f32_16x16x32_bf16 v[160:163], v[12:15], v[20:23], 0
	s_waitcnt lgkmcnt(1)
	v_fma_f32 v85, -v191, v107, v96
	s_waitcnt lgkmcnt(0)
	v_fma_f32 v86, v191, v84, v100
	v_fmac_f32_e32 v85, v190, v84
	v_fmac_f32_e32 v86, v190, v107
	v_fma_f32 v84, -v191, v86, v97
	v_cvt_pk_bf16_f32 v87, v85, v86
	v_fmac_f32_e32 v84, v190, v85
	v_fma_f32 v85, v191, v85, v101
	ds_write_b32 v205, v87 offset:12416
	v_fmac_f32_e32 v85, v190, v86
	v_fma_f32 v87, -v191, v85, v98
	v_fma_f32 v88, v191, v84, v102
	v_fmac_f32_e32 v88, v190, v85
	v_cvt_pk_bf16_f32 v86, v84, v85
	v_fmac_f32_e32 v87, v190, v84
	v_fma_f32 v96, -v191, v88, v99
	ds_write_b32 v205, v86 offset:12688
	v_mfma_f32_16x16x32_bf16 v[164:167], v[12:15], v[16:19], 0
	v_cvt_pk_bf16_f32 v84, v87, v88
	v_fmac_f32_e32 v96, v190, v87
	v_fmac_f32_e32 v103, v191, v87
	ds_write_b32 v205, v84 offset:12960
	v_fmac_f32_e32 v103, v190, v88
	v_mfma_f32_16x16x32_bf16 v[168:171], v[12:15], v[28:31], 0
	v_cvt_pk_bf16_f32 v84, v96, v103
	ds_write_b32 v205, v84 offset:13232
	ds_read_b128 v[84:87], v175 offset:48
	ds_read_b128 v[88:91], v175 offset:5168
	v_mfma_f32_16x16x32_bf16 v[64:67], v[12:15], v[32:35], 0
	s_waitcnt lgkmcnt(1)
	v_fma_f32 v84, -v191, v103, v84
	s_waitcnt lgkmcnt(0)
	v_fma_f32 v88, v191, v96, v88
	v_fmac_f32_e32 v84, v190, v96
	v_fmac_f32_e32 v88, v190, v103
	v_fma_f32 v85, -v191, v88, v85
	v_cvt_pk_bf16_f32 v96, v84, v88
	v_fmac_f32_e32 v85, v190, v84
	v_fma_f32 v84, v191, v84, v89
	ds_write_b32 v205, v96 offset:13504
	v_fmac_f32_e32 v84, v190, v88
	v_fma_f32 v86, -v191, v84, v86
	v_fma_f32 v89, v191, v85, v90
	v_cvt_pk_bf16_f32 v88, v85, v84
	v_fmac_f32_e32 v89, v190, v84
	ds_write_b32 v205, v88 offset:13776
	v_fmac_f32_e32 v86, v190, v85
	v_fma_f32 v88, -v191, v89, v87
	v_mfma_f32_16x16x32_bf16 v[68:71], v[12:15], v[36:39], 0
	v_cvt_pk_bf16_f32 v84, v86, v89
	v_fmac_f32_e32 v88, v190, v86
	v_fmac_f32_e32 v91, v191, v86
	ds_write_b32 v205, v84 offset:14048
	v_fmac_f32_e32 v91, v190, v89
	v_mfma_f32_16x16x32_bf16 v[72:75], v[12:15], v[40:43], 0
	v_cvt_pk_bf16_f32 v84, v88, v91
	ds_write_b32 v205, v84 offset:14320
	s_waitcnt lgkmcnt(0)
	ds_read_b128 v[84:87], v204 offset:10240
	ds_read_b128 v[96:99], v204 offset:10304
	ds_read_b128 v[100:103], v204 offset:10368
	ds_read_b128 v[104:107], v204 offset:10432
	s_waitcnt lgkmcnt(0)
	ds_write_b128 v201, v[128:131]
	ds_write_b128 v201, v[132:135] offset:1280
	ds_write_b128 v201, v[136:139] offset:2560
	ds_write_b128 v202, v[140:143]
	ds_write_b128 v201, v[144:147] offset:5120
	ds_write_b128 v201, v[148:151] offset:6400
	ds_write_b128 v201, v[152:155] offset:7680
	ds_write_b128 v203, v[156:159]
	s_waitcnt lgkmcnt(0)
	ds_read_b128 v[108:111], v175
	ds_read_b128 v[112:115], v175 offset:5120
	s_waitcnt lgkmcnt(13)
	v_mfma_f32_16x16x32_bf16 v[84:87], v[84:87], v[52:55], 0
	s_waitcnt lgkmcnt(1)
	v_fma_f32 v89, -v191, v91, v108
	s_waitcnt lgkmcnt(0)
	v_fma_f32 v90, v191, v88, v112
	v_fmac_f32_e32 v89, v190, v88
	v_fmac_f32_e32 v90, v190, v91
	v_fma_f32 v88, -v191, v90, v109
	v_cvt_pk_bf16_f32 v91, v89, v90
	v_fmac_f32_e32 v88, v190, v89
	v_fma_f32 v89, v191, v89, v113
	ds_write_b32 v205, v91 offset:10240
	v_fmac_f32_e32 v89, v190, v90
	v_fma_f32 v91, -v191, v89, v110
	v_fma_f32 v108, v191, v88, v114
	v_fmac_f32_e32 v108, v190, v89
	v_cvt_pk_bf16_f32 v90, v88, v89
	v_fmac_f32_e32 v91, v190, v88
	v_fma_f32 v112, -v191, v108, v111
	ds_write_b32 v205, v90 offset:10512
	v_mfma_f32_16x16x32_bf16 v[84:87], v[96:99], v[56:59], v[84:87]
	v_cvt_pk_bf16_f32 v88, v91, v108
	v_fmac_f32_e32 v112, v190, v91
	v_fmac_f32_e32 v115, v191, v91
	ds_write_b32 v205, v88 offset:10784
	v_fmac_f32_e32 v115, v190, v108
	v_mfma_f32_16x16x32_bf16 v[84:87], v[100:103], v[60:63], v[84:87]
	v_cvt_pk_bf16_f32 v88, v112, v115
	ds_write_b32 v205, v88 offset:11056
	ds_read_b128 v[88:91], v175 offset:16
	ds_read_b128 v[108:111], v175 offset:5136
	v_mfma_f32_16x16x32_bf16 v[76:79], v[12:15], v[44:47], 0
	s_waitcnt lgkmcnt(1)
	v_fma_f32 v88, -v191, v115, v88
	s_waitcnt lgkmcnt(0)
	v_fma_f32 v108, v191, v112, v108
	v_fmac_f32_e32 v88, v190, v112
	v_fmac_f32_e32 v108, v190, v115
	v_fma_f32 v89, -v191, v108, v89
	v_cvt_pk_bf16_f32 v112, v88, v108
	v_fmac_f32_e32 v89, v190, v88
	v_fma_f32 v88, v191, v88, v109
	ds_write_b32 v205, v112 offset:11328
	v_fmac_f32_e32 v88, v190, v108
	v_fma_f32 v90, -v191, v88, v90
	v_fma_f32 v109, v191, v89, v110
	v_cvt_pk_bf16_f32 v108, v89, v88
	v_fmac_f32_e32 v109, v190, v88
	ds_write_b32 v205, v108 offset:11600
	v_fmac_f32_e32 v90, v190, v89
	v_fma_f32 v108, -v191, v109, v91
	v_mfma_f32_16x16x32_bf16 v[80:83], v[12:15], v[48:51], 0
	v_cvt_pk_bf16_f32 v88, v90, v109
	v_fmac_f32_e32 v108, v190, v90
	v_fmac_f32_e32 v111, v191, v90
	ds_write_b32 v205, v88 offset:11872
	v_fmac_f32_e32 v111, v190, v109
	v_mfma_f32_16x16x32_bf16 v[24:27], v[206:209], v[60:63], v[24:27]
	v_cvt_pk_bf16_f32 v88, v108, v111
	ds_write_b32 v205, v88 offset:12144
	ds_read_b128 v[88:91], v175 offset:32
	ds_read_b128 v[112:115], v175 offset:5152
	v_mfma_f32_16x16x32_bf16 v[24:27], v[210:213], v[92:95], v[24:27]
	s_waitcnt lgkmcnt(1)
	v_fma_f32 v88, -v191, v111, v88
	s_waitcnt lgkmcnt(0)
	v_fma_f32 v96, v191, v108, v112
	v_fmac_f32_e32 v88, v190, v108
	v_fmac_f32_e32 v96, v190, v111
	v_fma_f32 v89, -v191, v96, v89
	v_cvt_pk_bf16_f32 v97, v88, v96
	v_fmac_f32_e32 v89, v190, v88
	v_fma_f32 v88, v191, v88, v113
	ds_write_b32 v205, v97 offset:12416
	v_fmac_f32_e32 v88, v190, v96
	v_fma_f32 v90, -v191, v88, v90
	v_fma_f32 v97, v191, v89, v114
	v_fmac_f32_e32 v97, v190, v88
	v_cvt_pk_bf16_f32 v96, v89, v88
	v_fmac_f32_e32 v90, v190, v89
	v_fma_f32 v108, -v191, v97, v91
	ds_write_b32 v205, v96 offset:12688
	s_nop 0
	v_cvt_pk_bf16_f32 v88, v90, v97
	v_fmac_f32_e32 v108, v190, v90
	v_fmac_f32_e32 v115, v191, v90
	ds_write_b32 v205, v88 offset:12960
	v_fmac_f32_e32 v115, v190, v97
	s_nop 0
	v_cvt_pk_bf16_f32 v88, v108, v115
	ds_write_b32 v205, v88 offset:13232
	ds_read_b128 v[88:91], v175 offset:48
	ds_read_b128 v[96:99], v175 offset:5168
	s_waitcnt lgkmcnt(1)
	v_fma_f32 v88, -v191, v115, v88
	s_waitcnt lgkmcnt(0)
	v_fma_f32 v96, v191, v108, v96
	v_fmac_f32_e32 v88, v190, v108
	v_fmac_f32_e32 v96, v190, v115
	v_fma_f32 v89, -v191, v96, v89
	v_cvt_pk_bf16_f32 v100, v88, v96
	v_fmac_f32_e32 v89, v190, v88
	v_fma_f32 v88, v191, v88, v97
	ds_write_b32 v205, v100 offset:13504
	v_fmac_f32_e32 v88, v190, v96
	v_fma_f32 v90, -v191, v88, v90
	v_fma_f32 v97, v191, v89, v98
	v_cvt_pk_bf16_f32 v96, v89, v88
	v_fmac_f32_e32 v97, v190, v88
	ds_write_b32 v205, v96 offset:13776
	v_fmac_f32_e32 v90, v190, v89
	v_fma_f32 v96, -v191, v97, v91
	s_nop 0
	v_cvt_pk_bf16_f32 v88, v90, v97
	v_fmac_f32_e32 v96, v190, v90
	v_fmac_f32_e32 v99, v191, v90
	ds_write_b32 v205, v88 offset:14048
	v_fmac_f32_e32 v99, v190, v97
	s_nop 0
	v_cvt_pk_bf16_f32 v88, v96, v99
	ds_write_b32 v205, v88 offset:14320
	s_waitcnt lgkmcnt(0)
	ds_read_b128 v[88:91], v204 offset:10240
	ds_read_b128 v[100:103], v204 offset:10304
	ds_read_b128 v[108:111], v204 offset:10368
	ds_read_b128 v[112:115], v204 offset:10432
	s_waitcnt lgkmcnt(0)
	ds_write_b128 v201, v[160:163]
	ds_write_b128 v201, v[164:167] offset:1280
	ds_write_b128 v201, v[168:171] offset:2560
	ds_write_b128 v202, v[64:67]
	ds_write_b128 v201, v[68:71] offset:5120
	ds_write_b128 v201, v[72:75] offset:6400
	ds_write_b128 v201, v[76:79] offset:7680
	ds_write_b128 v203, v[80:83]
	s_waitcnt lgkmcnt(0)
	ds_read_b128 v[16:19], v175
	ds_read_b128 v[28:31], v175 offset:5120
	s_waitcnt lgkmcnt(13)
	v_mfma_f32_16x16x32_bf16 v[36:39], v[88:91], v[52:55], 0
	s_waitcnt lgkmcnt(1)
	v_fma_f32 v16, -v191, v99, v16
	s_waitcnt lgkmcnt(0)
	v_fma_f32 v28, v191, v96, v28
	v_fmac_f32_e32 v16, v190, v96
	v_fmac_f32_e32 v28, v190, v99
	v_fma_f32 v17, -v191, v28, v17
	v_cvt_pk_bf16_f32 v32, v16, v28
	v_fmac_f32_e32 v17, v190, v16
	v_fma_f32 v16, v191, v16, v29
	ds_write_b32 v205, v32 offset:10240
	v_fmac_f32_e32 v16, v190, v28
	v_fma_f32 v18, -v191, v16, v18
	v_fma_f32 v29, v191, v17, v30
	v_cvt_pk_bf16_f32 v28, v17, v16
	v_fmac_f32_e32 v29, v190, v16
	ds_write_b32 v205, v28 offset:10512
	v_fmac_f32_e32 v18, v190, v17
	v_fma_f32 v28, -v191, v29, v19
	v_mfma_f32_16x16x32_bf16 v[36:39], v[100:103], v[56:59], v[36:39]
	v_cvt_pk_bf16_f32 v16, v18, v29
	v_fmac_f32_e32 v28, v190, v18
	v_fmac_f32_e32 v31, v191, v18
	ds_write_b32 v205, v16 offset:10784
	v_fmac_f32_e32 v31, v190, v29
	v_mfma_f32_16x16x32_bf16 v[36:39], v[108:111], v[60:63], v[36:39]
	v_cvt_pk_bf16_f32 v16, v28, v31
	ds_write_b32 v205, v16 offset:11056
	ds_read_b128 v[16:19], v175 offset:16
	ds_read_b128 v[32:35], v175 offset:5136
	v_mfma_f32_16x16x32_bf16 v[20:23], v[104:107], v[92:95], v[84:87]
	s_waitcnt lgkmcnt(1)
	v_fma_f32 v16, -v191, v31, v16
	s_waitcnt lgkmcnt(0)
	v_fma_f32 v29, v191, v28, v32
	v_fmac_f32_e32 v16, v190, v28
	v_fmac_f32_e32 v29, v190, v31
	v_fma_f32 v17, -v191, v29, v17
	v_cvt_pk_bf16_f32 v28, v16, v29
	v_fmac_f32_e32 v17, v190, v16
	v_fma_f32 v16, v191, v16, v33
	v_fmac_f32_e32 v16, v190, v29
	ds_write_b32 v205, v28 offset:11328
	v_fma_f32 v18, -v191, v16, v18
	v_cvt_pk_bf16_f32 v28, v17, v16
	v_fmac_f32_e32 v18, v190, v17
	v_fma_f32 v17, v191, v17, v34
	v_fmac_f32_e32 v17, v190, v16
	v_fma_f32 v32, -v191, v17, v19
	ds_write_b32 v205, v28 offset:11600
	s_nop 0
	v_cvt_pk_bf16_f32 v16, v18, v17
	v_fmac_f32_e32 v32, v190, v18
	v_fmac_f32_e32 v35, v191, v18
	ds_write_b32 v205, v16 offset:11872
	v_fmac_f32_e32 v35, v190, v17
	s_nop 0
	v_cvt_pk_bf16_f32 v16, v32, v35
	ds_write_b32 v205, v16 offset:12144
	ds_read_b128 v[16:19], v175 offset:32
	ds_read_b128 v[28:31], v175 offset:5152
	s_waitcnt lgkmcnt(1)
	v_fma_f32 v16, -v191, v35, v16
	s_waitcnt lgkmcnt(0)
	v_fma_f32 v28, v191, v32, v28
	v_fmac_f32_e32 v16, v190, v32
	v_fmac_f32_e32 v28, v190, v35
	v_fma_f32 v17, -v191, v28, v17
	v_cvt_pk_bf16_f32 v32, v16, v28
	v_fmac_f32_e32 v17, v190, v16
	v_fma_f32 v16, v191, v16, v29
	v_fmac_f32_e32 v16, v190, v28
	ds_write_b32 v205, v32 offset:12416
	v_fma_f32 v18, -v191, v16, v18
	v_cvt_pk_bf16_f32 v28, v17, v16
	v_fmac_f32_e32 v18, v190, v17
	v_fma_f32 v17, v191, v17, v30
	v_fmac_f32_e32 v17, v190, v16
	ds_write_b32 v205, v28 offset:12688
	v_fma_f32 v28, -v191, v17, v19
	s_nop 0
	v_cvt_pk_bf16_f32 v16, v18, v17
	v_fmac_f32_e32 v28, v190, v18
	v_fmac_f32_e32 v31, v191, v18
	ds_write_b32 v205, v16 offset:12960
	v_fmac_f32_e32 v31, v190, v17
	s_nop 0
	v_cvt_pk_bf16_f32 v16, v28, v31
	ds_write_b32 v205, v16 offset:13232
	ds_read_b128 v[16:19], v175 offset:48
	ds_read_b128 v[32:35], v175 offset:5168
	s_waitcnt lgkmcnt(1)
	v_fma_f32 v16, -v191, v31, v16
	v_fmac_f32_e32 v16, v190, v28
	s_waitcnt lgkmcnt(0)
	v_fma_f32 v28, v191, v28, v32
	v_fmac_f32_e32 v28, v190, v31
	v_fma_f32 v17, -v191, v28, v17
	v_cvt_pk_bf16_f32 v29, v16, v28
	v_fmac_f32_e32 v17, v190, v16
	v_fma_f32 v16, v191, v16, v33
	v_fmac_f32_e32 v16, v190, v28
	ds_write_b32 v205, v29 offset:13504
	v_fma_f32 v18, -v191, v16, v18
	v_cvt_pk_bf16_f32 v28, v17, v16
	v_fmac_f32_e32 v18, v190, v17
	v_fma_f32 v17, v191, v17, v34
	ds_write_b32 v205, v28 offset:13776
	v_fmac_f32_e32 v17, v190, v16
	v_mfma_f32_16x16x32_bf16 v[28:31], v[112:115], v[92:95], v[36:39]
	v_cvt_pk_bf16_f32 v16, v18, v17
	ds_write_b32 v205, v16 offset:14048
	v_fma_f32 v16, -v191, v17, v19
	v_fmac_f32_e32 v16, v190, v18
	v_fmac_f32_e32 v35, v191, v18
	v_fmac_f32_e32 v35, v190, v17
	v_cvt_pk_bf16_f32 v16, v16, v35
	ds_write_b32 v205, v16 offset:14320
	s_waitcnt lgkmcnt(0)
	ds_read_b128 v[16:19], v204 offset:10240
	ds_read_b128 v[32:35], v204 offset:10304
	s_waitcnt lgkmcnt(1)
	v_mfma_f32_16x16x32_bf16 v[16:19], v[16:19], v[52:55], 0
	s_waitcnt lgkmcnt(0)
	v_mfma_f32_16x16x32_bf16 v[16:19], v[32:35], v[56:59], v[16:19]
	ds_read_b128 v[32:35], v204 offset:10368
	ds_read_b128 v[36:39], v204 offset:10432
	s_waitcnt lgkmcnt(0)
	s_waitcnt lgkmcnt(1)
	v_mfma_f32_16x16x32_bf16 v[16:19], v[32:35], v[60:63], v[16:19]
	v_lshl_or_b32 v32, s10, 9, v182
	global_load_dwordx2 v[168:169], v32, s[92:93]
	v_mov_b32_e32 v32, 0
	s_waitcnt lgkmcnt(0)
	v_mfma_f32_16x16x32_bf16 v[16:19], v[36:39], v[92:95], v[16:19]
	v_mov_b32_e32 v33, 0
	v_mov_b32_e32 v34, 0
	v_mov_b32_e32 v36, 0
	v_mov_b32_e32 v35, 0
	s_and_saveexec_b64 s[4:5], vcc
	s_cbranch_execz .LBB0_1548
	v_lshl_add_u64 v[32:33], v[180:181], 0, v[176:177]
	global_load_dwordx4 v[32:35], v[32:33], off
